# early L2 write-back by arrivers 8,16,24,29 of each XCD
# baseline (speedup 1.0000x reference)
.LBB0_140:
	s_or_b64 exec, exec, s[8:9]
	v_cvt_f32_u32_e32 v4, v2
	s_waitcnt vmcnt(0)
	v_readfirstlane_b32 s3, v3
	v_sub_u32_e32 v3, 0, v2
	v_rcp_iflag_f32_e32 v4, v4
	v_add_u32_e32 v5, s3, v1
	v_mul_f32_e32 v4, 0x4f7ffffe, v4
	v_cvt_u32_f32_e32 v4, v4
	v_mul_lo_u32 v1, v3, v4
	v_mul_hi_u32 v1, v4, v1
	v_add_u32_e32 v1, v4, v1
	v_mul_hi_u32 v1, v5, v1
	v_mul_lo_u32 v3, v1, v2
	v_sub_u32_e32 v3, v5, v3
	v_add_u32_e32 v4, 1, v1
	v_cmp_ge_u32_e32 vcc, v3, v2
	s_nop 1
	v_cndmask_b32_e32 v1, v1, v4, vcc
	v_sub_u32_e32 v4, v3, v2
	v_cndmask_b32_e32 v3, v3, v4, vcc
	v_add_u32_e32 v4, 1, v1
	v_cmp_ge_u32_e32 vcc, v3, v2
	v_add_u32_e32 v3, 1, v5
	s_nop 0
	v_cndmask_b32_e32 v1, v1, v4, vcc
	v_mul_lo_u32 v4, v2, v1
	v_add_u32_e32 v2, v4, v2
	v_cmp_ne_u32_e32 vcc, v3, v2
	s_and_saveexec_b64 s[6:7], vcc
	s_xor_b64 s[6:7], exec, s[6:7]
	s_cbranch_execz .LBB0_154
	s_waitcnt lgkmcnt(0)
	v_mov_b32_e32 v0, 0x2000
	buffer_inv sc1
	v_readfirstlane_b32 s12, v5
	s_and_b32 s12, s12, 31
	s_cmp_eq_u32 s12, 8
	s_cbranch_scc1 .Lewb_do1
	s_cmp_eq_u32 s12, 16
	s_cbranch_scc1 .Lewb_do1
	s_cmp_eq_u32 s12, 24
	s_cbranch_scc1 .Lewb_do1
	s_cmp_eq_u32 s12, 29
	s_cbranch_scc0 .Lewb_skip1

.LBB0_939:
	s_or_b64 exec, exec, s[16:17]
	v_cvt_f32_u32_e32 v4, v2
	s_waitcnt vmcnt(0)
	v_readfirstlane_b32 s2, v3
	v_sub_u32_e32 v3, 0, v2
	v_rcp_iflag_f32_e32 v4, v4
	v_add_u32_e32 v5, s2, v1
	v_mul_f32_e32 v4, 0x4f7ffffe, v4
	v_cvt_u32_f32_e32 v4, v4
	v_mul_lo_u32 v1, v3, v4
	v_mul_hi_u32 v1, v4, v1
	v_add_u32_e32 v1, v4, v1
	v_mul_hi_u32 v1, v5, v1
	v_mul_lo_u32 v3, v1, v2
	v_sub_u32_e32 v3, v5, v3
	v_add_u32_e32 v4, 1, v1
	v_cmp_ge_u32_e32 vcc, v3, v2
	s_nop 1
	v_cndmask_b32_e32 v1, v1, v4, vcc
	v_sub_u32_e32 v4, v3, v2
	v_cndmask_b32_e32 v3, v3, v4, vcc
	v_add_u32_e32 v4, 1, v1
	v_cmp_ge_u32_e32 vcc, v3, v2
	v_add_u32_e32 v3, 1, v5
	s_nop 0
	v_cndmask_b32_e32 v1, v1, v4, vcc
	v_mul_lo_u32 v4, v2, v1
	v_add_u32_e32 v2, v4, v2
	v_cmp_ne_u32_e32 vcc, v3, v2
	s_and_saveexec_b64 s[8:9], vcc
	s_xor_b64 s[14:15], exec, s[8:9]
	s_cbranch_execz .LBB0_953
	s_waitcnt lgkmcnt(0)
	buffer_inv sc1
	v_readfirstlane_b32 s18, v5
	s_and_b32 s18, s18, 31
	s_cmp_eq_u32 s18, 8
	s_cbranch_scc1 .Lewb_do2
	s_cmp_eq_u32 s18, 16
	s_cbranch_scc1 .Lewb_do2
	s_cmp_eq_u32 s18, 24
	s_cbranch_scc1 .Lewb_do2
	s_cmp_eq_u32 s18, 29
	s_cbranch_scc0 .Lewb_skip2

.LBB0_1593:
	s_or_b64 exec, exec, s[18:19]
	v_cvt_f32_u32_e32 v4, v2
	s_waitcnt vmcnt(0)
	v_readfirstlane_b32 s2, v3
	v_sub_u32_e32 v3, 0, v2
	v_rcp_iflag_f32_e32 v4, v4
	v_add_u32_e32 v5, s2, v1
	v_mul_f32_e32 v4, 0x4f7ffffe, v4
	v_cvt_u32_f32_e32 v4, v4
	v_mul_lo_u32 v1, v3, v4
	v_mul_hi_u32 v1, v4, v1
	v_add_u32_e32 v1, v4, v1
	v_mul_hi_u32 v1, v5, v1
	v_mul_lo_u32 v3, v1, v2
	v_sub_u32_e32 v3, v5, v3
	v_add_u32_e32 v4, 1, v1
	v_cmp_ge_u32_e32 vcc, v3, v2
	s_nop 1
	v_cndmask_b32_e32 v1, v1, v4, vcc
	v_sub_u32_e32 v4, v3, v2
	v_cndmask_b32_e32 v3, v3, v4, vcc
	v_add_u32_e32 v4, 1, v1
	v_cmp_ge_u32_e32 vcc, v3, v2
	v_add_u32_e32 v3, 1, v5
	s_nop 0
	v_cndmask_b32_e32 v1, v1, v4, vcc
	v_mul_lo_u32 v4, v2, v1
	v_add_u32_e32 v2, v4, v2
	v_cmp_ne_u32_e32 vcc, v3, v2
	s_and_saveexec_b64 s[8:9], vcc
	s_xor_b64 s[16:17], exec, s[8:9]
	s_cbranch_execz .LBB0_1607
	s_waitcnt lgkmcnt(0)
	buffer_inv sc1
	v_readfirstlane_b32 s20, v5
	s_and_b32 s20, s20, 31
	s_cmp_eq_u32 s20, 8
	s_cbranch_scc1 .Lewb_do5
	s_cmp_eq_u32 s20, 16
	s_cbranch_scc1 .Lewb_do5
	s_cmp_eq_u32 s20, 24
	s_cbranch_scc1 .Lewb_do5
	s_cmp_eq_u32 s20, 29
	s_cbranch_scc0 .Lewb_skip5

.LBB0_1713:
	s_or_b64 exec, exec, s[16:17]
	v_cvt_f32_u32_e32 v4, v2
	s_waitcnt vmcnt(0)
	v_readfirstlane_b32 s8, v3
	v_sub_u32_e32 v3, 0, v2
	v_rcp_iflag_f32_e32 v4, v4
	v_add_u32_e32 v5, s8, v1
	v_mul_f32_e32 v4, 0x4f7ffffe, v4
	v_cvt_u32_f32_e32 v4, v4
	v_mul_lo_u32 v1, v3, v4
	v_mul_hi_u32 v1, v4, v1
	v_add_u32_e32 v1, v4, v1
	v_mul_hi_u32 v1, v5, v1
	v_mul_lo_u32 v3, v1, v2
	v_sub_u32_e32 v3, v5, v3
	v_add_u32_e32 v4, 1, v1
	v_cmp_ge_u32_e32 vcc, v3, v2
	s_nop 1
	v_cndmask_b32_e32 v1, v1, v4, vcc
	v_sub_u32_e32 v4, v3, v2
	v_cndmask_b32_e32 v3, v3, v4, vcc
	v_add_u32_e32 v4, 1, v1
	v_cmp_ge_u32_e32 vcc, v3, v2
	v_add_u32_e32 v3, 1, v5
	s_nop 0
	v_cndmask_b32_e32 v1, v1, v4, vcc
	v_mul_lo_u32 v4, v2, v1
	v_add_u32_e32 v2, v4, v2
	v_cmp_ne_u32_e32 vcc, v3, v2
	s_and_saveexec_b64 s[8:9], vcc
	s_xor_b64 s[14:15], exec, s[8:9]
	s_cbranch_execz .LBB0_1727
	s_waitcnt lgkmcnt(0)
	buffer_inv sc1
	v_readfirstlane_b32 s18, v5
	s_and_b32 s18, s18, 31
	s_cmp_eq_u32 s18, 8
	s_cbranch_scc1 .Lewb_do6
	s_cmp_eq_u32 s18, 16
	s_cbranch_scc1 .Lewb_do6
	s_cmp_eq_u32 s18, 24
	s_cbranch_scc1 .Lewb_do6
	s_cmp_eq_u32 s18, 29
	s_cbranch_scc0 .Lewb_skip6
